# attention: 3 LDS K/V stages with DMA two tiles ahead + all 8 K-fragment reads issued up front + XCD-local unit order
# speedup vs baseline: 1.0064x; 1.0064x over previous
; #define LAS __attribute__((address_space(3)))
; DI void attn_phase(const Params& p, unsigned char* smem) {
;     ...
;     for (int unit = blockIdx.x; unit < 2048; unit += gridDim.x) {
;         const int round = unit >> 8, i256 = unit & 255, bh = i256 >> 2, jj = i256 & 3;
;         const int qb = (round & 1) ? 24 - 8 * (round >> 1) + jj : 31 - 8 * (round >> 1) - jj;
;         const int b = bh >> 3, head = bh & 7;
;         const int q0 = qb * 128 + qg * 32;
;         bf16x8 Qf[4];
; #pragma unroll
;         for (int ks = 0; ks < 4; ++ks) Qf[ks] = *(const bf16x8*)(QK + (size_t)(b * 4096 + q0 + l31) * 2048 + head * 128 + comp * 64 + ks * 16 + hi * 8);
;         f32x16 O[4];
; #pragma unroll
;         for (int d = 0; d < 4; ++d)
; #pragma unroll
;             for (int i = 0; i < 16; ++i) O[d][i] = 0.f;
;         float mrun = 0.f, lrun = 0.f;
;         f32x16 NEGM;
; #pragma unroll
;         for (int i = 0; i < 16; ++i) NEGM[i] = 0.f;
;         const int ntile = 2 * (qb + 1) + 1;
;         auto dma_tile = [&](int j, int buf) __attribute__((always_inline)) {
;             const size_t krow0 = j == 0 ? (size_t)MR : (size_t)(b * 4096 + (j - 1) * 64);
; #pragma unroll
;             for (int i = 0; i < 2; ++i) {
;                 const int bi = wu * 2 + i;
;                 {
;                     const int key = 4 * bi + (lane >> 4), part = (lane & 15) ^ (key & 15);
;                     __builtin_amdgcn_global_load_lds((const unsigned*)(QK + (krow0 + key) * 2048 + 1024 + head * 128 + part * 8),
;                                                      (LAS unsigned*)(lds + buf * 16384 + bi * 1024), 16, 0, 0);
;                 }
;                 {
;                     const int dv = 8 * bi + (lane >> 3), ch = (lane & 7) ^ ((dv >> 1) & 7);
;                     __builtin_amdgcn_global_load_lds((const unsigned*)(VT + (size_t)(head * 128 + dv) * MP + krow0 + ch * 8),
;                                                      (LAS unsigned*)(lds + 32768 + buf * 16384 + bi * 1024), 16, 0, 0);
;                 }
;             }
;         };
;     ...
;         __syncthreads();
;         dma_tile(0, 0);
;         asm volatile("s_waitcnt vmcnt(0)" ::: "memory");
;         __syncthreads();
;         for (int j = 0; j < ntile; ++j) {
;             const int buf = j & 1;
;             if (j + 1 < ntile) dma_tile(j + 1, buf ^ 1);
.LBB0_1273:
	s_and_b32 s10, s44, 3
	s_ashr_i32 s19, s44, 6
	s_and_b32 s18, s44, 0x100
	s_and_b32 s19, s19, -8
	s_xor_b32 s20, s10, 31
	s_or_b32 s10, s10, 24
	s_cmp_eq_u32 s18, 0
	s_cselect_b32 s10, s20, s10
	s_sub_i32 s18, s10, s19
	s_lshl_b32 s10, s44, 7
	v_lshl_add_u32 v195, s18, 7, v179
	s_and_b32 s10, s10, 0x7000
	v_add_u32_e32 v1, s10, v195
	v_or_b32_e32 v168, v1, v153
	v_ashrrev_i32_e32 v169, 31, v168
	s_lshl_b32 s10, s44, 5
	v_lshlrev_b64 v[2:3], 12, v[168:169]
	s_and_b32 s19, s10, 0x380
	v_lshl_add_u64 v[2:3], s[34:35], 0, v[2:3]
	s_lshl_b32 s10, s19, 1
	v_lshl_add_u64 v[2:3], v[2:3], 0, s[10:11]
	v_lshl_add_u64 v[2:3], v[2:3], 0, v[158:159]
	v_lshl_add_u64 v[2:3], v[2:3], 0, v[160:161]
	s_mov_b32 m0, s36
	global_load_dwordx4 v[128:131], v[2:3], off
	global_load_dwordx4 v[132:135], v[2:3], off offset:32
	global_load_dwordx4 v[136:139], v[2:3], off offset:64
	global_load_dwordx4 v[140:143], v[2:3], off offset:96
	v_lshl_add_u64 v[2:3], v[146:147], 0, s[10:11]
	v_add_u32_e32 v1, s19, v180
	s_barrier
	global_load_lds_dwordx4 v[2:3], off
	v_mad_i64_i32 v[2:3], s[20:21], v1, s37, v[166:167]
	v_lshl_add_u64 v[170:171], v[2:3], 0, v[162:163]
	v_lshl_add_u64 v[2:3], v[170:171], 0, s[12:13]
	s_mov_b32 m0, s38
	v_add_u32_e32 v1, s19, v181
	global_load_lds_dwordx4 v[2:3], off
	v_lshl_add_u64 v[2:3], v[150:151], 0, s[10:11]
	s_mov_b32 m0, s39
	s_cmp_lt_i32 s18, -1
	global_load_lds_dwordx4 v[2:3], off
	v_mad_i64_i32 v[2:3], s[20:21], v1, s37, v[166:167]
	v_lshl_add_u64 v[172:173], v[2:3], 0, v[164:165]
	v_lshl_add_u64 v[2:3], v[172:173], 0, s[12:13]
	s_mov_b32 m0, s40
	s_nop 0
	global_load_lds_dwordx4 v[2:3], off
	s_waitcnt vmcnt(0)
	s_waitcnt vmcnt(0) lgkmcnt(0)
	s_barrier
	s_cbranch_scc1 .LBB0_1302
	v_mov_b32_e32 v14, v0
	v_mov_b32_e32 v15, v0
	s_lshl_b32 s46, s18, 1
	v_mov_b32_e32 v1, v0
	v_mov_b32_e32 v2, v0
	v_mov_b32_e32 v3, v0
	v_mov_b32_e32 v4, v0
	v_mov_b32_e32 v5, v0
	v_mov_b32_e32 v6, v0
	v_mov_b32_e32 v7, v0
	v_mov_b32_e32 v8, v0
	v_mov_b32_e32 v9, v0
	v_mov_b32_e32 v10, v0
	v_mov_b32_e32 v11, v0
	v_mov_b32_e32 v12, v0
	v_mov_b32_e32 v13, v0
	v_mov_b32_e32 v198, 0
	v_mov_b64_e32 v[30:31], v[14:15]
	v_mov_b64_e32 v[46:47], v[14:15]
	v_mov_b64_e32 v[62:63], v[14:15]
	v_mov_b64_e32 v[78:79], v[14:15]
	s_and_b32 s45, s31, 0x7000
	s_add_i32 s46, s46, 3
	v_or_b32_e32 v196, 31, v195
	v_or_b32_e32 v197, v195, v153
	v_lshl_add_u64 v[174:175], v[154:155], 0, s[10:11]
	v_lshl_add_u64 v[176:177], v[156:157], 0, s[10:11]
	s_mov_b32 s18, 0
	s_movk_i32 s47, 0xffe0
	v_mov_b64_e32 v[28:29], v[12:13]
	v_mov_b64_e32 v[26:27], v[10:11]
	v_mov_b64_e32 v[24:25], v[8:9]
	v_mov_b64_e32 v[22:23], v[6:7]
	v_mov_b64_e32 v[20:21], v[4:5]
	v_mov_b64_e32 v[18:19], v[2:3]
	v_mov_b64_e32 v[16:17], v[0:1]
	v_mov_b64_e32 v[44:45], v[12:13]
	v_mov_b64_e32 v[42:43], v[10:11]
	v_mov_b64_e32 v[40:41], v[8:9]
	v_mov_b64_e32 v[38:39], v[6:7]
	v_mov_b64_e32 v[36:37], v[4:5]
	v_mov_b64_e32 v[34:35], v[2:3]
	v_mov_b64_e32 v[32:33], v[0:1]
	v_mov_b64_e32 v[60:61], v[12:13]
	v_mov_b64_e32 v[58:59], v[10:11]
	v_mov_b64_e32 v[56:57], v[8:9]
	v_mov_b64_e32 v[54:55], v[6:7]
	v_mov_b64_e32 v[52:53], v[4:5]
	v_mov_b64_e32 v[50:51], v[2:3]
	v_mov_b64_e32 v[48:49], v[0:1]
	v_mov_b64_e32 v[76:77], v[12:13]
	v_mov_b64_e32 v[74:75], v[10:11]
	v_mov_b64_e32 v[72:73], v[8:9]
	v_mov_b64_e32 v[70:71], v[6:7]
	v_mov_b64_e32 v[68:69], v[4:5]
	v_mov_b64_e32 v[66:67], v[2:3]
	v_mov_b64_e32 v[64:65], v[0:1]
	v_mov_b32_e32 v2, 0
	v_mov_b32_e32 v80, 0
	v_mov_b32_e32 v81, v198
	v_mov_b32_e32 v82, v198
	v_mov_b32_e32 v83, v198
	v_mov_b32_e32 v84, v198
	v_mov_b32_e32 v85, v198
	v_mov_b32_e32 v86, v198
	v_mov_b32_e32 v87, v198
	v_mov_b32_e32 v88, v198
	v_mov_b32_e32 v89, v198
	v_mov_b32_e32 v90, v198
	v_mov_b32_e32 v91, v198
	v_mov_b32_e32 v92, v198
	v_mov_b32_e32 v93, v198
	v_mov_b32_e32 v94, v198
	v_mov_b32_e32 v95, v198
	s_mov_b32 s100, 0
	s_mov_b32 s101, 0x4000
	s_mov_b32 s99, 0x10000
	s_add_i32 s48, s18, 1
	s_add_i32 s19, s45, s47
	s_add_i32 s20, s19, 32
	s_ashr_i32 s21, s20, 31
	v_lshl_add_u64 v[4:5], s[20:21], 0, v[144:145]
	v_lshlrev_b64 v[4:5], 12, v[4:5]
	v_lshl_add_u64 v[4:5], v[174:175], 0, v[4:5]
	s_add_i32 s23, s101, s3
	v_lshl_add_u64 v[4:5], v[4:5], 0, s[14:15]
	s_mov_b32 m0, s23
	s_lshl_b64 s[24:25], s[20:21], 1
	global_load_lds_dwordx4 v[4:5], off
	v_lshl_add_u64 v[4:5], v[170:171], 0, s[24:25]
	s_add_i32 m0, s23, 0x8000
	s_add_i32 s19, s101, s30
	global_load_lds_dwordx4 v[4:5], off
	v_lshl_add_u64 v[4:5], s[20:21], 0, v[148:149]
	v_lshlrev_b64 v[4:5], 12, v[4:5]
	v_lshl_add_u64 v[4:5], v[176:177], 0, v[4:5]
	v_lshl_add_u64 v[4:5], v[4:5], 0, s[14:15]
	s_mov_b32 m0, s19
	s_nop 0
	global_load_lds_dwordx4 v[4:5], off
	v_lshl_add_u64 v[4:5], v[172:173], 0, s[24:25]
	s_add_i32 m0, s19, 0x8000
	s_nop 0
	global_load_lds_dwordx4 v[4:5], off
	s_branch .Lattn_head
; DI f32x16 mfma32(bf16x8 a, bf16x8 b, f32x16 c) { return __builtin_amdgcn_mfma_f32_32x32x16_bf16(a, b, c, 0, 0, 0); }
; DI void attn_phase(const Params& p, unsigned char* smem) {
;     ...
;         auto qk_half = [&](const bf16_t* kb, int kh, int ksw) __attribute__((always_inline)) {
;             f32x16 S = NEGM;
; #pragma unroll
;             for (int ks = 0; ks < 4; ++ks)
;                 S = mfma32(*(const bf16x8*)(kb + (kh * 32 + l31) * 128 + (((comp * 8 + ks * 2 + hi) ^ ksw) * 8)), Qf[ks], S);
;             return S;
;         };
;         auto softmax_half = [&](f32x16& S, f32x16* Spend, int j, int kh, int kbase, bool need_mask, bf16x8 (&P)[2]) __attribute__((always_inline)) {
;             if (need_mask) {
; #pragma unroll
;                 for (int i = 0; i < 16; ++i) {
;                     const int key = kh * 32 + 8 * (i >> 2) + 4 * hi + (i & 3);
;                     const bool vis = (j == 0) ? (key < 16) : (kbase + key <= q0 + l31);
;                     if (!vis) S[i] = -INFINITY;
;                 }
;             }
;     ...
;         for (int j = 0; j < ntile; ++j) {
;             const int buf = j & 1;
;             if (j + 1 < ntile) dma_tile(j + 1, buf ^ 1);
;             const int kbase = (j - 1) * 64;
;             const bool active = (j == 0) || (kbase <= q0 + 31);
;             if (active) {
;                 const bf16_t* kb = sK + buf * 64 * 128;
;                 const bf16_t* vb = sV + buf * 128 * 64;
;                 const bool need_mask = (j == 0) || (kbase + 63 > q0);
;                 const bool act1 = (j >= 1) && (kbase + 32 <= q0 + 31);
;                 const int ksw = l31 & 15, dsw = (l31 >> 1) & 7;
;                 f32x16 S0 = qk_half(kb, 0, ksw);
;                 bf16x8 P[2];
;                 if (act1) {
;                     f32x16 S1 = qk_half(kb, 1, ksw);
.LBB0_1275:
	s_mov_b32 s18, s48
	s_add_i32 s48, s18, 1
	s_mov_b32 s98, s100
	s_mov_b32 s100, s101
	s_mov_b32 s101, s99
	s_mov_b32 s99, s98
.Lattn_head:
	s_add_i32 s98, s18, 2
	s_cmp_ge_i32 s98, s46
	s_cselect_b32 s98, 0, 1
	s_cbranch_scc1 .LBB0_1277
	s_add_i32 s19, s45, s47
	s_add_i32 s20, s19, 96
	s_ashr_i32 s21, s20, 31
	v_lshl_add_u64 v[4:5], s[20:21], 0, v[144:145]
	v_lshlrev_b64 v[4:5], 12, v[4:5]
	v_lshl_add_u64 v[4:5], v[174:175], 0, v[4:5]
	s_add_i32 s23, s99, s3
	v_lshl_add_u64 v[4:5], v[4:5], 0, s[14:15]
	s_mov_b32 m0, s23
	s_lshl_b64 s[24:25], s[20:21], 1
	global_load_lds_dwordx4 v[4:5], off
	v_lshl_add_u64 v[4:5], v[170:171], 0, s[24:25]
	s_add_i32 m0, s23, 0x8000
	s_add_i32 s19, s99, s30
	global_load_lds_dwordx4 v[4:5], off
	v_lshl_add_u64 v[4:5], s[20:21], 0, v[148:149]
	v_lshlrev_b64 v[4:5], 12, v[4:5]
	v_lshl_add_u64 v[4:5], v[176:177], 0, v[4:5]
	v_lshl_add_u64 v[4:5], v[4:5], 0, s[14:15]
	s_mov_b32 m0, s19
	s_nop 0
	global_load_lds_dwordx4 v[4:5], off
	v_lshl_add_u64 v[4:5], v[172:173], 0, s[24:25]
	s_add_i32 m0, s19, 0x8000
	s_nop 0
	global_load_lds_dwordx4 v[4:5], off
.LBB0_1277:
	s_sub_i32 s19, s47, 32
	s_cmp_eq_u32 s18, 0
	s_cselect_b64 s[20:21], -1, 0
	v_cmp_le_i32_e32 vcc, s19, v196
	s_or_b64 s[24:25], s[20:21], vcc
	s_and_saveexec_b64 s[18:19], s[24:25]
	s_cbranch_execz .LBB0_1301
	s_mov_b32 s22, s100
	v_add_u32_e32 v12, s22, v192
	v_lshl_add_u32 v1, v182, 1, v12
	v_lshl_add_u32 v3, v183, 1, v12
	v_lshl_add_u32 v204, v184, 1, v12
	v_lshl_add_u32 v205, v185, 1, v12
	ds_read_b128 v[4:7], v1
	ds_read_b128 v[8:11], v3
	ds_read_b128 v[206:209], v204
	ds_read_b128 v[210:213], v205
	ds_read_b128 v[214:217], v1 offset:8192
	ds_read_b128 v[218:221], v3 offset:8192
	ds_read_b128 v[222:225], v204 offset:8192
	ds_read_b128 v[226:229], v205 offset:8192
	s_add_i32 s49, s22, 0
	s_add_i32 s22, s47, 31
	v_cmp_gt_i32_e32 vcc, s22, v195
	s_or_b64 s[22:23], s[20:21], vcc
	s_xor_b64 s[24:25], s[20:21], -1
	v_cmp_le_i32_e32 vcc, s47, v196
	s_waitcnt lgkmcnt(6)
	v_mfma_f32_32x32x16_bf16 v[96:111], v[4:7], v[128:131], v[80:95]
	s_and_b64 s[24:25], s[24:25], vcc
	v_mfma_f32_32x32x16_bf16 v[96:111], v[8:11], v[132:135], v[96:111]
	s_waitcnt lgkmcnt(4)
	v_mfma_f32_32x32x16_bf16 v[96:111], v[206:209], v[136:139], v[96:111]
	v_mfma_f32_32x32x16_bf16 v[96:111], v[210:213], v[140:143], v[96:111]
	s_and_saveexec_b64 s[26:27], s[24:25]
	s_xor_b64 s[24:25], exec, s[26:27]
	s_cbranch_execz .LBB0_1292
	v_mov_b64_e32 v[126:127], v[94:95]
	v_mov_b64_e32 v[124:125], v[92:93]
	v_mov_b64_e32 v[122:123], v[90:91]
	v_mov_b64_e32 v[120:121], v[88:89]
	v_mov_b64_e32 v[118:119], v[86:87]
	v_mov_b64_e32 v[116:117], v[84:85]
	v_mov_b64_e32 v[114:115], v[82:83]
	v_mov_b64_e32 v[112:113], v[80:81]
	s_waitcnt lgkmcnt(2)
	s_nop 0
	v_mfma_f32_32x32x16_bf16 v[112:127], v[214:217], v[128:131], v[112:127]
	v_mfma_f32_32x32x16_bf16 v[112:127], v[218:221], v[132:135], v[112:127]
	s_waitcnt lgkmcnt(0)
	v_mfma_f32_32x32x16_bf16 v[112:127], v[222:225], v[136:139], v[112:127]
	v_mfma_f32_32x32x16_bf16 v[112:127], v[226:229], v[140:143], v[112:127]
	s_and_saveexec_b64 s[26:27], s[22:23]
	s_cbranch_execz .LBB0_1283
	v_add_u32_e32 v1, s47, v152
	v_subrev_u32_e32 v3, 32, v1
	v_cmp_lt_i32_e32 vcc, v3, v197
	s_nop 1
	v_cndmask_b32_e32 v97, v194, v97, vcc
	v_cmp_le_i32_e32 vcc, v3, v197
	v_subrev_u32_e32 v3, 30, v1
	s_nop 0
	v_cndmask_b32_e32 v96, v194, v96, vcc
	v_cmp_le_i32_e32 vcc, v3, v197
	v_subrev_u32_e32 v3, 29, v1
	s_nop 0
	v_cndmask_b32_e32 v98, v194, v98, vcc
	v_cmp_le_i32_e32 vcc, v3, v197
	v_subrev_u32_e32 v3, 24, v1
	s_nop 0
	v_cndmask_b32_e32 v99, v194, v99, vcc
	v_cmp_le_i32_e32 vcc, v3, v197
	v_subrev_u32_e32 v3, 23, v1
	s_nop 0
	v_cndmask_b32_e32 v100, v194, v100, vcc
	v_cmp_le_i32_e32 vcc, v3, v197
	v_subrev_u32_e32 v3, 22, v1
	s_nop 0
	v_cndmask_b32_e32 v101, v194, v101, vcc
	v_cmp_le_i32_e32 vcc, v3, v197
	v_subrev_u32_e32 v3, 21, v1
	s_nop 0
	v_cndmask_b32_e32 v102, v194, v102, vcc
	v_cmp_le_i32_e32 vcc, v3, v197
	v_add_u32_e32 v3, -16, v1
	s_nop 0
	v_cndmask_b32_e32 v103, v194, v103, vcc
	v_cmp_le_i32_e32 vcc, v3, v197
	v_add_u32_e32 v3, -15, v1
	s_nop 0
	v_cndmask_b32_e32 v104, v194, v104, vcc
	v_cmp_le_i32_e32 vcc, v3, v197
	v_add_u32_e32 v3, -14, v1
	s_nop 0
	v_cndmask_b32_e32 v105, v194, v105, vcc
	v_cmp_le_i32_e32 vcc, v3, v197
	v_add_u32_e32 v3, -13, v1
	s_nop 0
	v_cndmask_b32_e32 v106, v194, v106, vcc
	v_cmp_le_i32_e32 vcc, v3, v197
	v_add_u32_e32 v3, -8, v1
	s_nop 0
	v_cndmask_b32_e32 v107, v194, v107, vcc
	v_cmp_le_i32_e32 vcc, v3, v197
	v_add_u32_e32 v3, -7, v1
	s_nop 0
	v_cndmask_b32_e32 v108, v194, v108, vcc
	v_cmp_le_i32_e32 vcc, v3, v197
	v_add_u32_e32 v3, -6, v1
	v_add_u32_e32 v1, -5, v1
	v_cndmask_b32_e32 v109, v194, v109, vcc
	v_cmp_le_i32_e32 vcc, v3, v197
	s_nop 1
	v_cndmask_b32_e32 v110, v194, v110, vcc
	v_cmp_gt_i32_e32 vcc, v1, v197
	s_and_saveexec_b64 s[28:29], vcc
	v_mov_b32_e32 v111, s41
	s_or_b64 exec, exec, s[28:29]

; DI void attn_phase(const Params& p, unsigned char* smem) {
;     ...
;             asm volatile("s_waitcnt vmcnt(0)" ::: "memory");
;             __syncthreads();
;         }
.LBB0_1301:
	s_or_b64 exec, exec, s[18:19]
	s_add_i32 s47, s47, 64
	s_cmp_eq_u32 s98, 0
	s_cbranch_scc1 .Lattn_wait_all
	s_waitcnt vmcnt(4) lgkmcnt(0)
	s_branch .Lattn_wait_done
.Lattn_wait_all:
	s_waitcnt vmcnt(0) lgkmcnt(0)
.Lattn_wait_done:
	s_cmp_eq_u32 s46, s48
	s_barrier
	s_cbranch_scc0 .LBB0_1275
	s_branch .LBB0_1303
